# mix0: blocks with bit 8 of the block id set run their gMLP tiles before their attention tiles (different mixers overlap on a CU)
# speedup vs baseline: 1.0037x; 1.0037x over previous
.LBB0_248:
	s_or_b64 exec, exec, s[0:1]
	s_cmpk_gt_i32 s2, 0xbff
	v_lshlrev_b32_e32 v156, 9, v131
	v_lshlrev_b32_e32 v159, 2, v134
	v_lshlrev_b32_e32 v158, 5, v131
	s_waitcnt lgkmcnt(0)
	s_barrier
	s_cbranch_scc1 .LBB0_261
	v_lshlrev_b32_e32 v4, 13, v135
	v_lshl_add_u32 v6, v134, 3, v138
	v_lshl_or_b32 v8, v134, 11, v4
	v_lshlrev_b32_e32 v10, 5, v138
	v_or3_b32 v77, v4, v137, v10
	v_lshl_or_b32 v102, v6, 2, v8
	v_add_u32_e32 v10, 0x60, v6
	v_add_u32_e32 v6, 0x70, v6
	v_and_b32_e32 v10, 0x7f, v10
	v_and_b32_e32 v6, 0x7f, v6
	v_lshl_or_b32 v103, v10, 2, v8
	v_lshl_or_b32 v104, v6, 2, v8
	v_add_u32_e32 v8, 8, v133
	v_and_b32_e32 v8, 0x78, v8
	v_lshlrev_b32_e32 v6, 9, v136
	v_lshlrev_b32_e32 v8, 2, v8
	v_or3_b32 v106, v4, v6, v8
	v_add_u32_e32 v8, 16, v133
	v_and_b32_e32 v8, 0x78, v8
	v_lshlrev_b32_e32 v6, 9, v132
	v_lshlrev_b32_e32 v8, 2, v8
	v_or3_b32 v108, v4, v6, v8
	v_add_u32_e32 v8, 24, v133
	v_xor_b32_e32 v0, v128, v131
	v_and_b32_e32 v8, 0x78, v8
	v_lshlrev_b32_e32 v1, 3, v0
	v_lshlrev_b32_e32 v6, 9, v130
	v_lshlrev_b32_e32 v8, 2, v8
	v_and_b32_e32 v0, 56, v1
	s_movk_i32 s0, 0x1e0
	v_or3_b32 v110, v4, v6, v8
	v_and_b32_e32 v6, 0x78, v1
	v_xor_b32_e32 v1, 1, v134
	v_and_or_b32 v2, v153, s0, v138
	v_cmp_gt_u32_e64 s[0:1], v1, v134
	v_xor_b32_e32 v1, 2, v134
	v_cmp_gt_u32_e64 s[22:23], v1, v134
	v_xor_b32_e32 v1, 3, v134
	v_cmp_gt_u32_e64 s[4:5], v1, v134
	v_bitop3_b32 v1, v134, v131, 15 bitop3:0x78
	v_lshlrev_b32_e32 v120, 4, v1
	v_bitop3_b32 v1, v134, v138, 4 bitop3:0x36
	v_lshlrev_b32_e32 v121, 4, v1
	v_bitop3_b32 v1, v134, v138, 8 bitop3:0x36
	v_lshlrev_b32_e32 v122, 4, v1
	v_bitop3_b32 v1, v134, v138, 12 bitop3:0x36
	v_lshlrev_b32_e32 v123, 4, v1
	v_xor_b32_e32 v1, v134, v131
	v_lshlrev_b32_e32 v1, 3, v1
	v_and_b32_e32 v124, 0x70, v1
	v_bitop3_b32 v1, v134, v131, 4 bitop3:0x36
	v_lshlrev_b32_e32 v1, 3, v1
	v_and_b32_e32 v125, 0x70, v1
	v_bitop3_b32 v1, v134, v131, 8 bitop3:0x36
	v_lshlrev_b32_e32 v1, 3, v1
	v_and_b32_e32 v126, 0x70, v1
	v_bitop3_b32 v1, v134, v131, 12 bitop3:0x36
	v_mov_b32_e32 v72, 0
	v_lshlrev_b32_e32 v1, 3, v1
	v_and_b32_e32 v127, 0x70, v1
	v_mul_u32_u24_e32 v1, 0x210, v138
	s_movk_i32 s8, 0x2100
	v_and_b32_e32 v10, 0x7f00, v158
	v_mov_b32_e32 v11, v72
	v_mad_u32_u24 v1, v135, s8, v1
	s_movk_i32 s8, 0xfe10
	v_lshl_add_u64 v[12:13], s[50:51], 0, v[10:11]
	v_lshlrev_b32_e32 v14, 1, v0
	v_mov_b32_e32 v15, v72
	s_add_u32 s30, s50, 0x9a00000
	v_lshlrev_b32_e32 v9, 5, v135
	v_mad_i32_i24 v16, v138, s8, v1
	v_lshl_add_u64 v[12:13], v[12:13], 0, v[14:15]
	s_mov_b64 s[8:9], 0x1080000
	v_lshl_add_u64 v[10:11], s[48:49], 0, v[10:11]
	s_addc_u32 s31, s51, 0
	v_bitop3_b32 v3, v128, v139, 3 bitop3:0x6c
	v_or_b32_e32 v4, 16, v9
	v_lshl_add_u64 v[78:79], v[12:13], 0, s[8:9]
	v_lshl_add_u64 v[10:11], v[10:11], 0, v[14:15]
	s_mov_b64 s[8:9], 0x2000000
	s_add_u32 s34, s50, 0xba00000
	v_lshlrev_b32_e32 v75, 7, v138
	v_lshlrev_b32_e32 v3, 4, v3
	v_lshlrev_b32_e32 v5, 7, v2
	v_lshlrev_b32_e32 v7, 4, v152
	v_lshlrev_b32_e32 v2, 3, v138
	v_or_b32_e32 v105, v134, v9
	v_or_b32_e32 v107, v136, v9
	v_or_b32_e32 v109, v132, v9
	v_or_b32_e32 v111, v130, v9
	v_or_b32_e32 v74, v4, v134
	v_or_b32_e32 v112, v136, v4
	v_or_b32_e32 v113, v132, v4
	v_or_b32_e32 v114, v130, v4
	v_lshlrev_b32_e32 v76, 4, v135
	v_lshlrev_b32_e32 v4, 3, v134
	v_and_b32_e32 v8, 0x7f000, v156
	v_mov_b32_e32 v118, 0x10000
	v_and_b32_e32 v9, 48, v131
	v_mul_u32_u24_e32 v17, 0x210, v134
	v_lshl_add_u64 v[80:81], v[10:11], 0, s[8:9]
	s_addc_u32 s35, s51, 0
	v_lshlrev_b32_e32 v10, 1, v6
	v_mov_b32_e32 v11, v72
	v_or_b32_e32 v115, v76, v138
	v_lshlrev_b32_e32 v116, 8, v138
	v_and_b32_e32 v117, 8, v4
	s_mov_b32 s29, 0
	v_cmp_eq_u32_e64 s[6:7], 0, v141
	v_lshl_or_b32 v119, v135, 2, v118
	v_lshl_add_u64 v[82:83], s[34:35], 0, v[10:11]
	s_xor_b32 s33, s2, 63
	s_mov_b64 s[38:39], 0x2000
	v_add_u32_e32 v141, 0x1000, v129
	s_mov_b64 s[46:47], 0x4000
	v_add_u32_e32 v142, 0x2000, v129
	s_mov_b64 s[52:53], 0x6000
	v_add_u32_e32 v143, 0x3000, v129
	v_or_b32_e32 v144, 0x4000, v129
	v_add_u32_e32 v145, 0x5000, v129
	v_add_u32_e32 v146, 0x6000, v129
	v_add_u32_e32 v147, 0x7000, v129
	s_mov_b64 s[56:57], 0x80
	v_or_b32_e32 v148, 0x8000, v129
	s_mov_b64 s[58:59], 0x2080
	v_add_u32_e32 v150, 0x9000, v129
	s_mov_b64 s[60:61], 0x4080
	v_add_u32_e32 v151, 0xa000, v129
	s_mov_b64 s[64:65], 0x6080
	v_add_u32_e32 v160, 0xb000, v129
	v_or_b32_e32 v161, 0xc000, v129
	v_add_u32_e32 v162, 0xd000, v129
	v_add_u32_e32 v163, 0xe000, v129
	v_add_u32_e32 v164, 0xf000, v129
	v_add_u32_e32 v165, v3, v5
	v_add_u32_e32 v166, v3, v75
	v_add_u32_e32 v167, v7, v5
	v_add_u32_e32 v168, v7, v75
	s_movk_i32 s84, 0x7fff
	s_mov_b32 s85, 0x7060302
	v_lshlrev_b32_e32 v84, 1, v4
	v_lshlrev_b32_e32 v86, 1, v6
	s_mov_b64 s[66:67], 0x8000
	s_mov_b64 s[70:71], 0x10000
	s_mov_b64 s[72:73], 0x18000
	v_lshlrev_b32_e32 v88, 1, v8
	v_lshlrev_b32_e32 v90, 1, v0
	s_mov_b64 s[74:75], 0x40000
	s_mov_b64 s[76:77], 0x80000
	s_mov_b64 s[78:79], 0xc0000
	s_mov_b32 s86, 0xc3200000
	v_add_u32_e32 v169, v1, v9
	v_add_u32_e32 v170, v16, v17
	s_mov_b32 s87, 0x5a00000
	v_add_u32_e32 v171, 0x400, v102
	v_lshlrev_b32_e32 v92, 1, v2
	v_mbcnt_hi_u32_b32 v172, -1, v155
	s_mov_b32 s88, s2
	s_and_b32 s98, s2, 0x100
	s_lshl_b32 s98, s98, 3
	s_cmp_eq_u32 s3, 0x200
	s_cselect_b32 s98, s98, 0
	s_add_i32 s88, s88, s98
	s_branch .LBB0_252

.LBB0_251:
	s_add_i32 s88, s88, s3
	s_sub_i32 s33, s33, s3
	s_cmpk_lt_i32 s88, 0xc00
	s_cbranch_scc1 .Lmy_m0_chk
	s_cmp_eq_u32 s98, 0
	s_cbranch_scc1 .LBB0_261
	s_sub_i32 s88, s88, 0xc00
.Lmy_m0_chk:
	s_add_i32 s100, s2, s98
	s_cmp_eq_u32 s88, s100
	s_cbranch_scc1 .LBB0_261

	.amdhsa_kernel _Z14fwd_megakernel6Params
		.amdhsa_group_segment_fixed_size 65568
		.amdhsa_private_segment_fixed_size 0
		.amdhsa_kernarg_size 448
		.amdhsa_user_sgpr_count 2
		.amdhsa_user_sgpr_dispatch_ptr 0
		.amdhsa_user_sgpr_queue_ptr 0
		.amdhsa_user_sgpr_kernarg_segment_ptr 1
		.amdhsa_user_sgpr_dispatch_id 0
		.amdhsa_user_sgpr_kernarg_preload_length 0
		.amdhsa_user_sgpr_kernarg_preload_offset 0
		.amdhsa_user_sgpr_private_segment_size 0
		.amdhsa_uses_dynamic_stack 0
		.amdhsa_enable_private_segment 0
		.amdhsa_system_sgpr_workgroup_id_x 1
		.amdhsa_system_sgpr_workgroup_id_y 0
		.amdhsa_system_sgpr_workgroup_id_z 0
		.amdhsa_system_sgpr_workgroup_info 0
		.amdhsa_system_vgpr_workitem_id 2
		.amdhsa_next_free_vgpr 256
		.amdhsa_next_free_sgpr 102
		.amdhsa_accum_offset 256
		.amdhsa_reserve_vcc 1
		.amdhsa_float_round_mode_32 0
		.amdhsa_float_round_mode_16_64 0
		.amdhsa_float_denorm_mode_32 3
		.amdhsa_float_denorm_mode_16_64 3
		.amdhsa_dx10_clamp 1
		.amdhsa_ieee_mode 1
		.amdhsa_fp16_overflow 0
		.amdhsa_tg_split 0
		.amdhsa_exception_fp_ieee_invalid_op 0
		.amdhsa_exception_fp_denorm_src 0
		.amdhsa_exception_fp_ieee_div_zero 0
		.amdhsa_exception_fp_ieee_overflow 0
		.amdhsa_exception_fp_ieee_underflow 0
		.amdhsa_exception_fp_ieee_inexact 0
		.amdhsa_exception_int_div_zero 0
	.end_amdhsa_kernel

amdhsa.kernels:
  - .agpr_count:     0
    .args:
      - .offset:         0
        .size:           192
        .value_kind:     by_value
      - .offset:         192
        .size:           4
        .value_kind:     hidden_block_count_x
      - .offset:         196
        .size:           4
        .value_kind:     hidden_block_count_y
      - .offset:         200
        .size:           4
        .value_kind:     hidden_block_count_z
      - .offset:         204
        .size:           2
        .value_kind:     hidden_group_size_x
      - .offset:         206
        .size:           2
        .value_kind:     hidden_group_size_y
      - .offset:         208
        .size:           2
        .value_kind:     hidden_group_size_z
      - .offset:         210
        .size:           2
        .value_kind:     hidden_remainder_x
      - .offset:         212
        .size:           2
        .value_kind:     hidden_remainder_y
      - .offset:         214
        .size:           2
        .value_kind:     hidden_remainder_z
      - .offset:         232
        .size:           8
        .value_kind:     hidden_global_offset_x
      - .offset:         240
        .size:           8
        .value_kind:     hidden_global_offset_y
      - .offset:         248
        .size:           8
        .value_kind:     hidden_global_offset_z
      - .offset:         256
        .size:           2
        .value_kind:     hidden_grid_dims
      - .offset:         280
        .size:           8
        .value_kind:     hidden_multigrid_sync_arg
    .group_segment_fixed_size: 65568
    .kernarg_segment_align: 8
    .kernarg_segment_size: 448
    .language:       OpenCL C
    .language_version:
      - 2
      - 0
    .max_flat_workgroup_size: 256
    .name:           _Z14fwd_megakernel6Params
    .private_segment_fixed_size: 0
    .sgpr_count:     108
    .sgpr_spill_count: 65
    .symbol:         _Z14fwd_megakernel6Params.kd
    .uniform_work_group_size: 1
    .uses_dynamic_stack: false
    .vgpr_count:     256
    .vgpr_spill_count: 0
    .wavefront_size: 64
